# stack9 with s_sleep removed from the grid-barrier poll loops (faster release detection)
# baseline (speedup 1.0000x reference)
; DEVI unsigned xb_ld(unsigned* p)              { return __hip_atomic_load(p, __ATOMIC_RELAXED, __HIP_MEMORY_SCOPE_AGENT); }
; DEVI void xcd_barrier_complete(unsigned* bar, unsigned x, unsigned& nloc, unsigned& nx) {
;     ...
;     for (;;) {
;         sum = 0u; cnt = 0u; mine = 0u;
; #pragma unroll
;         for (unsigned j = 0; j < 16; ++j) { const unsigned c = xb_ld(&bar[XB_XCNT(j)]); sum += c; cnt += (c > 0u) ? 1u : 0u; mine = (j == x) ? c : mine; }
;         if (sum == G) break;
;         __builtin_amdgcn_s_sleep(1);
;         if ((++sp & 255u) == 0u) { if (xb_ld(&bar[XB_TMO])) break; if (sp > XB_SPIN_CAP) { atomicAdd(&bar[XB_TMO], 1u); break; } }
;     }
.LBB0_150:
	global_load_dword v15, v16, s[4:5] sc1
	s_waitcnt lgkmcnt(0)
	global_load_dword v0, v16, s[6:7] sc1
	global_load_dword v1, v16, s[8:9] sc1
	global_load_dword v2, v16, s[10:11] sc1
	global_load_dword v3, v16, s[12:13] sc1
	global_load_dword v4, v16, s[14:15] sc1
	global_load_dword v5, v16, s[16:17] sc1
	global_load_dword v6, v16, s[18:19] sc1
	global_load_dword v7, v16, s[20:21] sc1
	global_load_dword v8, v16, s[22:23] sc1
	global_load_dword v9, v16, s[24:25] sc1
	global_load_dword v10, v16, s[26:27] sc1
	global_load_dword v11, v16, s[28:29] sc1
	global_load_dword v12, v16, s[30:31] sc1
	global_load_dword v13, v16, s[34:35] sc1
	global_load_dword v14, v16, s[36:37] sc1
	s_mov_b64 s[38:39], -1
	s_mov_b64 s[40:41], -1
	s_waitcnt vmcnt(14)
	v_add_u32_e32 v17, v0, v15
	s_waitcnt vmcnt(13)
	v_add_u32_e32 v17, v17, v1
	s_waitcnt vmcnt(12)
	v_add_u32_e32 v17, v17, v2
	s_waitcnt vmcnt(11)
	v_add_u32_e32 v17, v17, v3
	s_waitcnt vmcnt(10)
	v_add_u32_e32 v17, v17, v4
	s_waitcnt vmcnt(9)
	v_add_u32_e32 v17, v17, v5
	s_waitcnt vmcnt(8)
	v_add_u32_e32 v17, v17, v6
	s_waitcnt vmcnt(7)
	v_add_u32_e32 v17, v17, v7
	s_waitcnt vmcnt(6)
	v_add_u32_e32 v17, v17, v8
	s_waitcnt vmcnt(5)
	v_add_u32_e32 v17, v17, v9
	s_waitcnt vmcnt(4)
	v_add_u32_e32 v17, v17, v10
	s_waitcnt vmcnt(3)
	v_add_u32_e32 v17, v17, v11
	s_waitcnt vmcnt(2)
	v_add_u32_e32 v17, v17, v12
	s_waitcnt vmcnt(1)
	v_add_u32_e32 v17, v17, v13
	s_waitcnt vmcnt(0)
	v_add_u32_e32 v17, v17, v14
	v_cmp_eq_u32_e32 vcc, s89, v17
	s_cbranch_vccnz .LBB0_149
	s_and_b32 s38, s48, 0xff
	s_cmp_eq_u32 s38, 0
	s_mov_b64 s[38:39], -1
	s_mov_b64 s[42:43], -1
	s_cbranch_scc0 .LBB0_154
	global_load_dword v17, v16, s[2:3] sc1
	s_waitcnt vmcnt(0)
	v_cmp_eq_u32_e32 vcc, 0, v17
	s_cbranch_vccnz .LBB0_156
	s_mov_b64 s[42:43], 0

.LBB0_168:
	s_and_b32 s18, s22, 0xff
	s_mov_b64 s[16:17], -1
	s_cmp_lg_u32 s18, 0
	s_mov_b64 s[20:21], -1
	s_cbranch_scc1 .LBB0_171
	global_load_dword v2, v0, s[8:9] sc1
	s_waitcnt vmcnt(0)
	v_cmp_eq_u32_e32 vcc, 0, v2
	s_cbranch_vccnz .LBB0_173
	s_mov_b64 s[20:21], 0
	s_mov_b64 s[18:19], -1

.LBB0_189:
	s_and_b32 s16, s22, 0xff
	s_cmp_lg_u32 s16, 0
	s_mov_b64 s[18:19], -1
	s_cbranch_scc1 .LBB0_192
	global_load_dword v1, v0, s[8:9] sc1
	s_waitcnt vmcnt(0)
	v_cmp_eq_u32_e32 vcc, 0, v1
	s_cbranch_vccnz .LBB0_194
	s_mov_b64 s[18:19], 0
	s_mov_b64 s[16:17], -1

; DEVI unsigned xb_ld(unsigned* p)              { return __hip_atomic_load(p, __ATOMIC_RELAXED, __HIP_MEMORY_SCOPE_AGENT); }
; DEVI void xcd_barrier_complete(unsigned* bar, unsigned x, unsigned& nloc, unsigned& nx) {
;     ...
;     for (;;) {
;         sum = 0u; cnt = 0u; mine = 0u;
; #pragma unroll
;         for (unsigned j = 0; j < 16; ++j) { const unsigned c = xb_ld(&bar[XB_XCNT(j)]); sum += c; cnt += (c > 0u) ? 1u : 0u; mine = (j == x) ? c : mine; }
;         if (sum == G) break;
;         __builtin_amdgcn_s_sleep(1);
;         if ((++sp & 255u) == 0u) { if (xb_ld(&bar[XB_TMO])) break; if (sp > XB_SPIN_CAP) { atomicAdd(&bar[XB_TMO], 1u); break; } }
;     }
.LBB0_1447:
	global_load_dword v15, v16, s[6:7] sc1
	s_waitcnt lgkmcnt(0)
	global_load_dword v0, v16, s[8:9] sc1
	global_load_dword v1, v16, s[10:11] sc1
	global_load_dword v2, v16, s[12:13] sc1
	global_load_dword v3, v16, s[14:15] sc1
	global_load_dword v4, v16, s[16:17] sc1
	global_load_dword v5, v16, s[18:19] sc1
	global_load_dword v6, v16, s[20:21] sc1
	global_load_dword v7, v16, s[22:23] sc1
	global_load_dword v8, v16, s[24:25] sc1
	global_load_dword v9, v16, s[26:27] sc1
	global_load_dword v10, v16, s[28:29] sc1
	global_load_dword v11, v16, s[30:31] sc1
	global_load_dword v12, v16, s[34:35] sc1
	global_load_dword v13, v16, s[36:37] sc1
	global_load_dword v14, v16, s[38:39] sc1
	s_mov_b64 s[40:41], -1
	s_mov_b64 s[42:43], -1
	s_waitcnt vmcnt(14)
	v_add_u32_e32 v17, v0, v15
	s_waitcnt vmcnt(13)
	v_add_u32_e32 v17, v17, v1
	s_waitcnt vmcnt(12)
	v_add_u32_e32 v17, v17, v2
	s_waitcnt vmcnt(11)
	v_add_u32_e32 v17, v17, v3
	s_waitcnt vmcnt(10)
	v_add_u32_e32 v17, v17, v4
	s_waitcnt vmcnt(9)
	v_add_u32_e32 v17, v17, v5
	s_waitcnt vmcnt(8)
	v_add_u32_e32 v17, v17, v6
	s_waitcnt vmcnt(7)
	v_add_u32_e32 v17, v17, v7
	s_waitcnt vmcnt(6)
	v_add_u32_e32 v17, v17, v8
	s_waitcnt vmcnt(5)
	v_add_u32_e32 v17, v17, v9
	s_waitcnt vmcnt(4)
	v_add_u32_e32 v17, v17, v10
	s_waitcnt vmcnt(3)
	v_add_u32_e32 v17, v17, v11
	s_waitcnt vmcnt(2)
	v_add_u32_e32 v17, v17, v12
	s_waitcnt vmcnt(1)
	v_add_u32_e32 v17, v17, v13
	s_waitcnt vmcnt(0)
	v_add_u32_e32 v17, v17, v14
	v_cmp_eq_u32_e32 vcc, s89, v17
	s_cbranch_vccnz .LBB0_1446
	s_and_b32 s40, s50, 0xff
	s_cmp_eq_u32 s40, 0
	s_mov_b64 s[40:41], -1
	s_mov_b64 s[48:49], -1
	s_cbranch_scc0 .LBB0_1451
	global_load_dword v17, v16, s[4:5] sc1
	s_waitcnt vmcnt(0)
	v_cmp_eq_u32_e32 vcc, 0, v17
	s_cbranch_vccnz .LBB0_1453
	s_mov_b64 s[48:49], 0

.LBB0_1465:
	s_and_b32 s20, s24, 0xff
	s_mov_b64 s[18:19], -1
	s_cmp_lg_u32 s20, 0
	s_mov_b64 s[22:23], -1
	s_cbranch_scc1 .LBB0_1468
	global_load_dword v2, v0, s[10:11] sc1
	s_waitcnt vmcnt(0)
	v_cmp_eq_u32_e32 vcc, 0, v2
	s_cbranch_vccnz .LBB0_1470
	s_mov_b64 s[22:23], 0
	s_mov_b64 s[20:21], -1

.LBB0_1482:
	s_and_b32 s18, s24, 0xff
	s_cmp_lg_u32 s18, 0
	s_mov_b64 s[20:21], -1
	s_cbranch_scc1 .LBB0_1485
	global_load_dword v1, v0, s[10:11] sc1
	s_waitcnt vmcnt(0)
	v_cmp_eq_u32_e32 vcc, 0, v1
	s_cbranch_vccnz .LBB0_1487
	s_mov_b64 s[20:21], 0
	s_mov_b64 s[18:19], -1

; DEVI unsigned xb_ld(unsigned* p)              { return __hip_atomic_load(p, __ATOMIC_RELAXED, __HIP_MEMORY_SCOPE_AGENT); }
; DEVI void xcd_barrier_complete(unsigned* bar, unsigned x, unsigned& nloc, unsigned& nx) {
;     ...
;     for (;;) {
;         sum = 0u; cnt = 0u; mine = 0u;
; #pragma unroll
;         for (unsigned j = 0; j < 16; ++j) { const unsigned c = xb_ld(&bar[XB_XCNT(j)]); sum += c; cnt += (c > 0u) ? 1u : 0u; mine = (j == x) ? c : mine; }
;         if (sum == G) break;
;         __builtin_amdgcn_s_sleep(1);
;         if ((++sp & 255u) == 0u) { if (xb_ld(&bar[XB_TMO])) break; if (sp > XB_SPIN_CAP) { atomicAdd(&bar[XB_TMO], 1u); break; } }
;     }
.LBB0_2754:
	global_load_dword v15, v16, s[4:5] sc1
	s_waitcnt lgkmcnt(0)
	global_load_dword v0, v16, s[6:7] sc1
	global_load_dword v1, v16, s[8:9] sc1
	global_load_dword v2, v16, s[10:11] sc1
	global_load_dword v3, v16, s[14:15] sc1
	global_load_dword v4, v16, s[16:17] sc1
	global_load_dword v5, v16, s[18:19] sc1
	global_load_dword v6, v16, s[20:21] sc1
	global_load_dword v7, v16, s[22:23] sc1
	global_load_dword v8, v16, s[24:25] sc1
	global_load_dword v9, v16, s[26:27] sc1
	global_load_dword v10, v16, s[28:29] sc1
	global_load_dword v11, v16, s[30:31] sc1
	global_load_dword v12, v16, s[34:35] sc1
	global_load_dword v13, v16, s[36:37] sc1
	global_load_dword v14, v16, s[38:39] sc1
	s_mov_b64 s[40:41], -1
	s_mov_b64 s[42:43], -1
	s_waitcnt vmcnt(14)
	v_add_u32_e32 v17, v0, v15
	s_waitcnt vmcnt(13)
	v_add_u32_e32 v17, v17, v1
	s_waitcnt vmcnt(12)
	v_add_u32_e32 v17, v17, v2
	s_waitcnt vmcnt(11)
	v_add_u32_e32 v17, v17, v3
	s_waitcnt vmcnt(10)
	v_add_u32_e32 v17, v17, v4
	s_waitcnt vmcnt(9)
	v_add_u32_e32 v17, v17, v5
	s_waitcnt vmcnt(8)
	v_add_u32_e32 v17, v17, v6
	s_waitcnt vmcnt(7)
	v_add_u32_e32 v17, v17, v7
	s_waitcnt vmcnt(6)
	v_add_u32_e32 v17, v17, v8
	s_waitcnt vmcnt(5)
	v_add_u32_e32 v17, v17, v9
	s_waitcnt vmcnt(4)
	v_add_u32_e32 v17, v17, v10
	s_waitcnt vmcnt(3)
	v_add_u32_e32 v17, v17, v11
	s_waitcnt vmcnt(2)
	v_add_u32_e32 v17, v17, v12
	s_waitcnt vmcnt(1)
	v_add_u32_e32 v17, v17, v13
	s_waitcnt vmcnt(0)
	v_add_u32_e32 v17, v17, v14
	v_cmp_eq_u32_e32 vcc, s89, v17
	s_cbranch_vccnz .LBB0_2753
	s_and_b32 s40, s50, 0xff
	s_cmp_eq_u32 s40, 0
	s_mov_b64 s[40:41], -1
	s_mov_b64 s[48:49], -1
	s_cbranch_scc0 .LBB0_2758
	global_load_dword v17, v16, s[2:3] sc1
	s_waitcnt vmcnt(0)
	v_cmp_eq_u32_e32 vcc, 0, v17
	s_cbranch_vccnz .LBB0_2760
	s_mov_b64 s[48:49], 0

.LBB0_2772:
	s_and_b32 s20, s24, 0xff
	s_mov_b64 s[18:19], -1
	s_cmp_lg_u32 s20, 0
	s_mov_b64 s[22:23], -1
	s_cbranch_scc1 .LBB0_2775
	global_load_dword v2, v0, s[8:9] sc1
	s_waitcnt vmcnt(0)
	v_cmp_eq_u32_e32 vcc, 0, v2
	s_cbranch_vccnz .LBB0_2777
	s_mov_b64 s[22:23], 0
	s_mov_b64 s[20:21], -1

.LBB0_2789:
	s_and_b32 s18, s24, 0xff
	s_cmp_lg_u32 s18, 0
	s_mov_b64 s[20:21], -1
	s_cbranch_scc1 .LBB0_2792
	global_load_dword v1, v0, s[8:9] sc1
	s_waitcnt vmcnt(0)
	v_cmp_eq_u32_e32 vcc, 0, v1
	s_cbranch_vccnz .LBB0_2794
	s_mov_b64 s[20:21], 0
	s_mov_b64 s[18:19], -1
